# ret_out score/PV LDS operand reads hoisted (10 in flight), GLU bias loads batched, packed accumulator reset, ret_kv K loads pipelined
# speedup vs baseline: 1.0000x; 1.0000x over previous
; template <class Epi, class Sched, bool ALIGN_EPI = false, bool SP2 = false>
; __device__ __forceinline__ void gemm_phase(PG8_LAS unsigned char* lds, const Gemm g, const Sched& S, const Epi& E) {
;     ...
;         const bool has_next = S.next(ui + 1, nxt);
;         const char* nA = has_next ? (const char*)g.A + (size_t)nxt.pm * tstep : cA; const char* nB = has_next ? (const char*)g.Bt + (size_t)nxt.pn * tstep : cB;
;         for (int t = 0; t < nt; t += 2) {
;             const bool last = (t == nt - 2);
;             const char* a1 = cA + (size_t)(t + 1) * kstep;
;             const char* a2 = last ? nA : cA + (size_t)(t + 2) * kstep; const char* b2 = last ? nB : cB + (size_t)(t + 2) * kstep;
;             const char* a3 = a2 + kstep; const char* b3 = b2 + kstep;
;             if (last && has_next) S.a_ready(nxt);
;             if (last) E.pre(cur, wid, lane);
;     __device__ __forceinline__ void finish(f32x4 (&acc)[2][2][4][2], const Pre&) const {
; #pragma unroll
;         for (int a = 0; a < 2; ++a)
; #pragma unroll
;             for (int b = 0; b < 2; ++b)
; #pragma unroll
;                 for (int m = 0; m < 4; ++m)
; #pragma unroll
;                     for (int n = 0; n < 2; ++n) acc[a][b][m][n] = (f32x4){0.f, 0.f, 0.f, 0.f};
;     }
.LBB0_243:
	s_ashr_i32 s49, s48, 31
	s_lshl_b64 s[6:7], s[48:49], 19
	s_add_u32 s50, s10, s6
	s_addc_u32 s51, s11, s7
	s_and_b64 s[6:7], s[36:37], exec
	s_cselect_b32 s38, s51, s5
	s_cselect_b32 s39, s50, s4
	s_ashr_i32 s47, s46, 31
	s_lshl_b64 s[6:7], s[46:47], 19
	s_add_u32 s52, s12, s6
	v_readlane_b32 s6, v255, 3
	s_addc_u32 s53, s6, s7
	s_and_b64 s[6:7], s[36:37], exec
	s_cselect_b32 s49, s53, s1
	s_cselect_b32 s55, s52, s0
	s_lshl_b32 s47, s56, 8
	v_add_u32_e32 v0, s47, v198
	v_ashrrev_i32_e32 v1, 31, v0
	v_lshlrev_b64 v[2:3], 6, v[0:1]
	v_or_b32_e32 v0, 16, v0
	v_ashrrev_i32_e32 v1, 31, v0
	s_add_u32 s4, s4, 0x40080
	v_lshlrev_b64 v[0:1], 6, v[0:1]
	s_addc_u32 s5, s5, 0
	v_lshl_add_u64 v[128:129], v[160:161], 0, v[0:1]
	s_add_u32 s56, s0, 0x100
	v_mov_b32_e32 v0, 0
	v_lshl_add_u64 v[130:131], v[160:161], 0, v[2:3]
	s_addc_u32 s57, s1, 0
	s_mov_b32 s58, -2
	v_mov_b32_e32 v1, 0
	v_pk_mov_b32 v[2:3], v[0:1], v[0:1]
	v_pk_mov_b32 v[4:5], v[0:1], v[0:1]
	v_pk_mov_b32 v[6:7], v[0:1], v[0:1]
	v_pk_mov_b32 v[8:9], v[0:1], v[0:1]
	v_pk_mov_b32 v[10:11], v[0:1], v[0:1]
	v_pk_mov_b32 v[12:13], v[0:1], v[0:1]
	v_pk_mov_b32 v[14:15], v[0:1], v[0:1]
	v_pk_mov_b32 v[16:17], v[0:1], v[0:1]
	v_pk_mov_b32 v[18:19], v[0:1], v[0:1]
	v_pk_mov_b32 v[20:21], v[0:1], v[0:1]
	v_pk_mov_b32 v[22:23], v[0:1], v[0:1]
	v_pk_mov_b32 v[24:25], v[0:1], v[0:1]
	v_pk_mov_b32 v[26:27], v[0:1], v[0:1]
	v_pk_mov_b32 v[28:29], v[0:1], v[0:1]
	v_pk_mov_b32 v[30:31], v[0:1], v[0:1]
	v_pk_mov_b32 v[32:33], v[0:1], v[0:1]
	v_pk_mov_b32 v[34:35], v[0:1], v[0:1]
	v_pk_mov_b32 v[36:37], v[0:1], v[0:1]
	v_pk_mov_b32 v[38:39], v[0:1], v[0:1]
	v_pk_mov_b32 v[40:41], v[0:1], v[0:1]
	v_pk_mov_b32 v[42:43], v[0:1], v[0:1]
	v_pk_mov_b32 v[44:45], v[0:1], v[0:1]
	v_pk_mov_b32 v[46:47], v[0:1], v[0:1]
	v_pk_mov_b32 v[48:49], v[0:1], v[0:1]
	v_pk_mov_b32 v[50:51], v[0:1], v[0:1]
	v_pk_mov_b32 v[52:53], v[0:1], v[0:1]
	v_pk_mov_b32 v[54:55], v[0:1], v[0:1]
	v_pk_mov_b32 v[56:57], v[0:1], v[0:1]
	v_pk_mov_b32 v[58:59], v[0:1], v[0:1]
	v_pk_mov_b32 v[60:61], v[0:1], v[0:1]
	v_pk_mov_b32 v[62:63], v[0:1], v[0:1]
	v_pk_mov_b32 v[64:65], v[0:1], v[0:1]
	v_pk_mov_b32 v[66:67], v[0:1], v[0:1]
	v_pk_mov_b32 v[68:69], v[0:1], v[0:1]
	v_pk_mov_b32 v[70:71], v[0:1], v[0:1]
	v_pk_mov_b32 v[72:73], v[0:1], v[0:1]
	v_pk_mov_b32 v[74:75], v[0:1], v[0:1]
	v_pk_mov_b32 v[76:77], v[0:1], v[0:1]
	v_pk_mov_b32 v[78:79], v[0:1], v[0:1]
	v_pk_mov_b32 v[80:81], v[0:1], v[0:1]
	v_pk_mov_b32 v[82:83], v[0:1], v[0:1]
	v_pk_mov_b32 v[84:85], v[0:1], v[0:1]
	v_pk_mov_b32 v[86:87], v[0:1], v[0:1]
	v_pk_mov_b32 v[88:89], v[0:1], v[0:1]
	v_pk_mov_b32 v[90:91], v[0:1], v[0:1]
	v_pk_mov_b32 v[92:93], v[0:1], v[0:1]
	v_pk_mov_b32 v[94:95], v[0:1], v[0:1]
	v_pk_mov_b32 v[96:97], v[0:1], v[0:1]
	v_pk_mov_b32 v[98:99], v[0:1], v[0:1]
	v_pk_mov_b32 v[100:101], v[0:1], v[0:1]
	v_pk_mov_b32 v[102:103], v[0:1], v[0:1]
	v_pk_mov_b32 v[104:105], v[0:1], v[0:1]
	v_pk_mov_b32 v[106:107], v[0:1], v[0:1]
	v_pk_mov_b32 v[108:109], v[0:1], v[0:1]
	v_pk_mov_b32 v[110:111], v[0:1], v[0:1]
	v_pk_mov_b32 v[112:113], v[0:1], v[0:1]
	v_pk_mov_b32 v[114:115], v[0:1], v[0:1]
	v_pk_mov_b32 v[116:117], v[0:1], v[0:1]
	v_pk_mov_b32 v[118:119], v[0:1], v[0:1]
	v_pk_mov_b32 v[120:121], v[0:1], v[0:1]
	v_pk_mov_b32 v[122:123], v[0:1], v[0:1]
	v_pk_mov_b32 v[124:125], v[0:1], v[0:1]
	v_pk_mov_b32 v[126:127], v[0:1], v[0:1]
	s_branch .LBB0_245

; #define LAS __attribute__((address_space(3)))
; __device__ __forceinline__ unsigned pk2(float lo, float hi) { return pg8::cvt_pk_bf16(lo, hi); }
; __device__ __forceinline__ float ret_lg2(int h) { return log2f(1.0f - exp2f(-5.0f - (float)h)); }
; template <int NR, bool ZETA> __device__ __forceinline__ void ret_load_R(const bf16* Z, int r0, int c0, LAS unsigned char* dst, int tid, float lg2) {
; #pragma unroll
;     for (int it = 0; it < NR / 32; ++it) { const int ch = it * NTHR + tid, r = ch >> 4, c = ch & 15;
;         u32x4 v = *(const u32x4*)(Z + (size_t)(r0 + r) * IW + c0 + c * 8);
;         if (ZETA) { const float zs = __builtin_amdgcn_exp2f((float)(127 - r) * lg2); float f[8]; unpack8(v, f);
;             v.x = pk2(f[0] * zs, f[1] * zs); v.y = pk2(f[2] * zs, f[3] * zs); v.z = pk2(f[4] * zs, f[5] * zs); v.w = pk2(f[6] * zs, f[7] * zs); }
;         *(LAS u32x4*)(dst + (r * 136 + c * 8) * 2) = v; }
; }
; __device__ __forceinline__ void ret_kv(const Args& a, int unit, LAS unsigned char* lds, int tid, int lane, int wave) {
;     const bf16* Z = (const bf16*)(a.ws + WS_HZ);
;     const int n = unit & 63, bh = unit >> 6, h = bh & 3, b = bh >> 2, r0 = b * SEQ + n * 128, fr = lane & 15, fq = lane >> 4;
;     const float lg2 = ret_lg2(h);
;     ret_load_R<128, true>(Z, r0, 768 + h * 128, lds + OFF_KS, tid, lg2);
;     ret_load_R<128, false>(Z, r0, 1280 + h * 128, lds + OFF_VT, tid, lg2);
;     __syncthreads();
.LBB0_1263:
	s_bfe_u32 s1, s4, 0x20006
	v_cvt_f32_ubyte0_e32 v0, s1
	v_sub_f32_e32 v0, 0xc0a00000, v0
	v_cmp_gt_f32_e32 vcc, s87, v0
	s_lshl_b32 s0, s4, 5
	s_lshl_b32 s5, s4, 7
	v_cndmask_b32_e32 v1, 0, v192, vcc
	v_add_f32_e32 v0, v0, v1
	s_and_b32 s0, s0, 0xffffe000
	s_and_b32 s5, s5, 0x1f80
	v_exp_f32_e32 v0, v0
	s_or_b32 s0, s0, s5
	s_and_b64 s[28:29], vcc, exec
	s_cselect_b32 s5, 0xffffffc0, 0
	v_ldexp_f32 v0, v0, s5
	v_sub_f32_e32 v1, 1.0, v0
	v_cmp_gt_f32_e32 vcc, s33, v1
	s_and_b64 s[28:29], vcc, exec
	s_cselect_b32 s5, 32, 0
	s_lshl_b32 s1, s1, 8
	v_lshlrev_b32_e32 v0, 3, v76
	s_add_u32 s28, s8, s1
	v_and_b32_e32 v0, 0x78, v0
	s_addc_u32 s29, s9, 0
	v_lshlrev_b32_e32 v144, 1, v0
	v_ashrrev_i32_e32 v16, 4, v76
	v_lshl_add_u64 v[10:11], s[28:29], 0, v[144:145]
	v_add_u32_e32 v2, s0, v16
	v_mad_i64_i32 v[12:13], s[28:29], v2, s84, v[10:11]
	global_load_dwordx4 v[2:5], v[12:13], off offset:1536
	v_ldexp_f32 v1, v1, s5
	v_add_u32_e32 v7, 0x200, v76
	v_sub_u32_e32 v8, 0x7f, v16
	v_log_f32_e32 v1, v1
	v_ashrrev_i32_e32 v18, 4, v7
	v_cvt_f32_i32_e32 v7, v8
	v_cndmask_b32_e32 v6, 0, v193, vcc
	v_sub_f32_e32 v1, v1, v6
	v_add_u32_e32 v8, s0, v18
	v_mul_f32_e32 v6, v1, v7
	v_exp_f32_e32 v6, v6
	v_mad_i64_i32 v[14:15], s[28:29], v8, s84, v[10:11]
	global_load_dwordx4 v[118:121], v[14:15], off offset:1536
	s_movk_i32 s5, 0x88
	v_lshrrev_b32_e32 v26, 2, v66
	v_lshlrev_b32_e32 v28, 3, v66
	s_movk_i32 s16, 0x110
	v_lshlrev_b32_e32 v27, 2, v66
	v_and_b32_e32 v28, 24, v28
	v_and_b32_e32 v144, 48, v66
	s_waitcnt vmcnt(1)
	v_lshlrev_b32_e32 v7, 16, v2
	v_and_b32_e32 v2, 0xffff0000, v2
	v_lshlrev_b32_e32 v8, 16, v3
	v_and_b32_e32 v3, 0xffff0000, v3
	v_lshlrev_b32_e32 v9, 16, v4
	v_and_b32_e32 v4, 0xffff0000, v4
	v_lshlrev_b32_e32 v17, 16, v5
	v_and_b32_e32 v5, 0xffff0000, v5
	v_mul_f32_e32 v7, v6, v7
	v_mul_f32_e32 v2, v6, v2
	v_mul_f32_e32 v8, v6, v8
	v_mul_f32_e32 v3, v6, v3
	v_mul_f32_e32 v9, v6, v9
	v_mul_f32_e32 v4, v6, v4
	v_mul_f32_e32 v5, v6, v5
	v_mul_f32_e32 v17, v6, v17
	v_cvt_pk_bf16_f32 v2, v7, v2
	v_cvt_pk_bf16_f32 v3, v8, v3
	v_cvt_pk_bf16_f32 v4, v9, v4
	v_cvt_pk_bf16_f32 v5, v17, v5
	v_add_u32_e32 v17, 0x400, v76
	v_ashrrev_i32_e32 v20, 4, v17
	v_mad_u64_u32 v[16:17], s[28:29], v16, s5, v[0:1]
	v_sub_u32_e32 v17, 0x7f, v18
	v_cvt_f32_i32_e32 v19, v17
	v_lshl_add_u32 v22, v16, 1, 0
	v_add_u32_e32 v16, s0, v20
	ds_write_b128 v22, v[2:5] offset:17408
	v_mul_f32_e32 v19, v1, v19
	v_exp_f32_e32 v19, v19
	v_mad_i64_i32 v[16:17], s[28:29], v16, s84, v[10:11]
	global_load_dwordx4 v[122:125], v[16:17], off offset:1536
	s_waitcnt vmcnt(1)
	v_lshlrev_b32_e32 v2, 16, v118
	v_and_b32_e32 v3, 0xffff0000, v118
	v_lshlrev_b32_e32 v4, 16, v119
	v_and_b32_e32 v5, 0xffff0000, v119
	v_lshlrev_b32_e32 v6, 16, v120
	v_and_b32_e32 v7, 0xffff0000, v120
	v_lshlrev_b32_e32 v8, 16, v121
	v_and_b32_e32 v9, 0xffff0000, v121
	v_mul_f32_e32 v2, v19, v2
	v_mul_f32_e32 v3, v19, v3
	v_mul_f32_e32 v4, v19, v4
	v_mul_f32_e32 v5, v19, v5
	v_mul_f32_e32 v6, v19, v6
	v_mul_f32_e32 v7, v19, v7
	v_mul_f32_e32 v8, v19, v8
	v_mul_f32_e32 v9, v19, v9
	v_cvt_pk_bf16_f32 v2, v2, v3
	v_cvt_pk_bf16_f32 v3, v4, v5
	v_cvt_pk_bf16_f32 v4, v6, v7
	v_cvt_pk_bf16_f32 v5, v8, v9
	v_add_u32_e32 v19, 0x600, v76
	v_ashrrev_i32_e32 v23, 4, v19
	v_mad_u64_u32 v[18:19], s[28:29], v18, s5, v[0:1]
	v_sub_u32_e32 v19, 0x7f, v20
	v_cvt_f32_i32_e32 v21, v19
	v_lshl_add_u32 v24, v18, 1, 0
	v_add_u32_e32 v18, s0, v23
	v_mad_i64_i32 v[18:19], s[0:1], v18, s84, v[10:11]
	global_load_dwordx4 v[118:121], v[18:19], off offset:1536
	v_mul_f32_e32 v10, v1, v21
	v_exp_f32_e32 v10, v10
	ds_write_b128 v24, v[2:5] offset:17408
	s_waitcnt vmcnt(1)
	v_lshlrev_b32_e32 v2, 16, v122
	v_and_b32_e32 v3, 0xffff0000, v122
	v_lshlrev_b32_e32 v4, 16, v123
	v_and_b32_e32 v5, 0xffff0000, v123
	v_lshlrev_b32_e32 v6, 16, v124
	v_and_b32_e32 v7, 0xffff0000, v124
	v_lshlrev_b32_e32 v8, 16, v125
	v_and_b32_e32 v9, 0xffff0000, v125
	v_mul_f32_e32 v2, v10, v2
	v_mul_f32_e32 v3, v10, v3
	v_mul_f32_e32 v4, v10, v4
	v_mul_f32_e32 v5, v10, v5
	v_mul_f32_e32 v6, v10, v6
	v_mul_f32_e32 v7, v10, v7
	v_mul_f32_e32 v8, v10, v8
	v_mul_f32_e32 v9, v10, v9
	v_cvt_pk_bf16_f32 v2, v2, v3
	v_cvt_pk_bf16_f32 v3, v4, v5
	v_cvt_pk_bf16_f32 v4, v6, v7
	v_cvt_pk_bf16_f32 v5, v8, v9
	v_sub_u32_e32 v10, 0x7f, v23
	v_cvt_f32_i32_e32 v21, v10
	v_mad_u64_u32 v[10:11], s[0:1], v20, s5, v[0:1]
	v_lshl_add_u32 v25, v10, 1, 0
	v_mul_f32_e32 v1, v1, v21
	global_load_dwordx4 v[18:21], v[18:19], off offset:2560
	v_exp_f32_e32 v1, v1
	ds_write_b128 v25, v[2:5] offset:17408
	s_waitcnt vmcnt(1)
	v_lshlrev_b32_e32 v2, 16, v118
	v_and_b32_e32 v3, 0xffff0000, v118
	v_lshlrev_b32_e32 v4, 16, v119
	v_and_b32_e32 v5, 0xffff0000, v119
	v_lshlrev_b32_e32 v6, 16, v120
	v_and_b32_e32 v7, 0xffff0000, v120
	v_lshlrev_b32_e32 v8, 16, v121
	v_and_b32_e32 v9, 0xffff0000, v121
	v_mul_f32_e32 v2, v1, v2
	v_mul_f32_e32 v3, v1, v3
	v_mul_f32_e32 v4, v1, v4
	v_mul_f32_e32 v5, v1, v5
	v_mul_f32_e32 v6, v1, v6
	v_mul_f32_e32 v7, v1, v7
	v_mul_f32_e32 v8, v1, v8
	v_mul_f32_e32 v1, v1, v9
	v_cvt_pk_bf16_f32 v2, v2, v3
	v_cvt_pk_bf16_f32 v3, v4, v5
	v_cvt_pk_bf16_f32 v4, v6, v7
	v_cvt_pk_bf16_f32 v5, v8, v1
	global_load_dwordx4 v[6:9], v[12:13], off offset:2560
	global_load_dwordx4 v[10:13], v[14:15], off offset:2560
	s_nop 0
	global_load_dwordx4 v[14:17], v[16:17], off offset:2560
	s_nop 0
	s_nop 0
	v_lshrrev_b32_e32 v1, 1, v76
	v_and_b32_e32 v29, 24, v1
	v_mad_u64_u32 v[0:1], s[0:1], v23, s5, v[0:1]
	v_and_or_b32 v56, v26, 3, v29
	s_lshl_b32 s1, s26, 5
	v_mad_u32_u24 v1, v56, s16, 0
	s_and_b32 s0, s1, 0x60
	v_add_u32_e32 v26, v1, v28
	s_and_b32 s5, s1, 0xffffff80
	s_or_b32 s1, s1, 0x60
	v_and_or_b32 v23, v27, 12, s0
	v_lshl_add_u32 v0, v0, 1, 0
	v_add_u32_e32 v57, s5, v26
	v_lshlrev_b32_e32 v58, 1, v23
	v_add_u32_e32 v59, s1, v26
	v_add_u32_e32 v48, v1, v58
	ds_write_b128 v0, v[2:5] offset:17408
	s_waitcnt vmcnt(2)
	ds_write_b128 v22, v[6:9] offset:52224
	s_waitcnt vmcnt(1)
	ds_write_b128 v24, v[10:13] offset:52224
	s_waitcnt vmcnt(0)
	ds_write_b128 v25, v[14:17] offset:52224
	s_waitcnt vmcnt(0)
	ds_write_b128 v0, v[18:21] offset:52224
	s_waitcnt lgkmcnt(0)
	s_barrier
; #define MFMA16(X, Y, ACC) ACC = __builtin_amdgcn_mfma_f32_16x16x32_bf16(X, Y, ACC, 0, 0, 0)
; __device__ __forceinline__ void ret_kv(const Args& a, int unit, LAS unsigned char* lds, int tid, int lane, int wave) {
;     ...
;     const int eb = (wave & 3) * 32, dh = (wave >> 2) * 64;
;     f32x4 acc[2][4];
; #pragma unroll
;     for (int i = 0; i < 2; ++i)
; #pragma unroll
;         for (int j = 0; j < 4; ++j) acc[i][j] = (f32x4){0.f, 0.f, 0.f, 0.f};
; #pragma unroll
;     for (int ks = 0; ks < 4; ++ks) {
;         bf16x8 vf[2], kf[4];
; #pragma unroll
;         for (int i = 0; i < 2; ++i) vf[i] = tr_frag(lds + OFF_VT, 272, 32 * ks, eb + i * 16, lane);
; #pragma unroll
;         for (int j = 0; j < 4; ++j) kf[j] = tr_frag(lds + OFF_KS, 272, 32 * ks, dh + j * 16, lane);
; #pragma unroll
;         for (int i = 0; i < 2; ++i)
; #pragma unroll
;             for (int j = 0; j < 4; ++j) MFMA16(kf[j], vf[i], acc[i][j]);
;         asm volatile("" ::: "memory");
;     }
;     float* KV = (float*)(a.ws + WS_KV) + (size_t)unit * 16384;
; #pragma unroll
;     for (int i = 0; i < 2; ++i)
; #pragma unroll
;         for (int j = 0; j < 4; ++j) *(f32x4*)(KV + (size_t)(eb + i * 16 + fr) * 128 + dh + j * 16 + 4 * fq) = acc[i][j];
;     __syncthreads();
	ds_read_b64_tr_b16 v[2:3], v57 offset:18496
	ds_read_b64_tr_b16 v[0:1], v57 offset:17408
	ds_read_b64_tr_b16 v[4:5], v57 offset:17440
	ds_read_b64_tr_b16 v[6:7], v57 offset:18528
	ds_read_b64_tr_b16 v[10:11], v48 offset:53312
	ds_read_b64_tr_b16 v[8:9], v48 offset:52224
	ds_read_b64_tr_b16 v[14:15], v48 offset:53344
	ds_read_b64_tr_b16 v[12:13], v48 offset:52256
	ds_read_b64_tr_b16 v[16:17], v57 offset:17472
	ds_read_b64_tr_b16 v[18:19], v57 offset:18560
	ds_read_b64_tr_b16 v[24:25], v59 offset:17408
	ds_read_b64_tr_b16 v[26:27], v59 offset:18496
	s_waitcnt lgkmcnt(6)
	v_mfma_f32_16x16x32_bf16 v[20:23], v[0:3], v[8:11], 0
	ds_read_b64_tr_b16 v[38:39], v57 offset:27200
	ds_read_b64_tr_b16 v[36:37], v57 offset:26112
	ds_read_b64_tr_b16 v[42:43], v48 offset:62016
	ds_read_b64_tr_b16 v[40:41], v48 offset:60928
	ds_read_b64_tr_b16 v[44:45], v57 offset:26144
	ds_read_b64_tr_b16 v[46:47], v57 offset:27232
	v_add_u32_e32 v60, s18, v58
	v_mfma_f32_16x16x32_bf16 v[28:31], v[4:7], v[8:11], 0
	s_lshl_b32 s1, s26, 4
	s_ashr_i32 s5, s4, 31
	s_and_b32 s28, s1, 0xffffffc0
	s_waitcnt lgkmcnt(8)
	v_mfma_f32_16x16x32_bf16 v[32:35], v[16:19], v[8:11], 0
	s_lshl_b64 s[4:5], s[4:5], 16
	s_waitcnt lgkmcnt(6)
	v_mfma_f32_16x16x32_bf16 v[8:11], v[24:27], v[8:11], 0
	v_mfma_f32_16x16x32_bf16 v[0:3], v[0:3], v[12:15], 0
	v_mfma_f32_16x16x32_bf16 v[4:7], v[4:7], v[12:15], 0
	v_mfma_f32_16x16x32_bf16 v[16:19], v[16:19], v[12:15], 0
	v_mfma_f32_16x16x32_bf16 v[12:15], v[24:27], v[12:15], 0
	ds_read_b64_tr_b16 v[26:27], v48 offset:62048
	ds_read_b64_tr_b16 v[24:25], v48 offset:60960
	ds_read_b64_tr_b16 v[48:49], v57 offset:26176
	ds_read_b64_tr_b16 v[50:51], v57 offset:27264
	ds_read_b64_tr_b16 v[52:53], v59 offset:26112
	ds_read_b64_tr_b16 v[54:55], v59 offset:27200
	s_waitcnt lgkmcnt(8)
	v_mfma_f32_16x16x32_bf16 v[20:23], v[36:39], v[40:43], v[20:23]
	s_waitcnt lgkmcnt(6)
	v_mfma_f32_16x16x32_bf16 v[28:31], v[44:47], v[40:43], v[28:31]
	s_waitcnt lgkmcnt(2)
	v_mfma_f32_16x16x32_bf16 v[32:35], v[48:51], v[40:43], v[32:35]
	s_waitcnt lgkmcnt(0)
	v_mfma_f32_16x16x32_bf16 v[8:11], v[52:55], v[40:43], v[8:11]
	v_mov_b32_e32 v40, 0x4400
	v_mad_u32_u24 v40, v56, s16, v40
	v_add3_u32 v61, s18, v40, v58
	v_mfma_f32_16x16x32_bf16 v[0:3], v[36:39], v[24:27], v[0:3]
	v_add_u32_e32 v42, v60, v40
	ds_read_b64_tr_b16 v[38:39], v57 offset:35904
	ds_read_b64_tr_b16 v[36:37], v57 offset:34816
	v_mfma_f32_16x16x32_bf16 v[4:7], v[44:47], v[24:27], v[4:7]
	ds_read_b64_tr_b16 v[40:41], v42
	ds_read_b64_tr_b16 v[42:43], v42 offset:1088
	ds_read_b64_tr_b16 v[44:45], v57 offset:34848
	ds_read_b64_tr_b16 v[46:47], v57 offset:35936
	v_mfma_f32_16x16x32_bf16 v[16:19], v[48:51], v[24:27], v[16:19]
	v_mfma_f32_16x16x32_bf16 v[12:15], v[52:55], v[24:27], v[12:15]
	ds_read_b64_tr_b16 v[24:25], v61 offset:32
	ds_read_b64_tr_b16 v[26:27], v61 offset:1120
	ds_read_b64_tr_b16 v[48:49], v57 offset:34880
	ds_read_b64_tr_b16 v[50:51], v57 offset:35968
	ds_read_b64_tr_b16 v[52:53], v59 offset:34816
	ds_read_b64_tr_b16 v[54:55], v59 offset:35904
	s_waitcnt lgkmcnt(8)
	v_mfma_f32_16x16x32_bf16 v[20:23], v[36:39], v[40:43], v[20:23]
	s_waitcnt lgkmcnt(4)
	v_mfma_f32_16x16x32_bf16 v[0:3], v[36:39], v[24:27], v[0:3]
	v_mov_b32_e32 v36, 0x6600
	v_mad_u32_u24 v36, v56, s16, v36
	v_readlane_b32 s16, v252, 48
	v_mfma_f32_16x16x32_bf16 v[28:31], v[44:47], v[40:43], v[28:31]
	v_readlane_b32 s17, v252, 49
	s_add_u32 s4, s16, s4
	s_addc_u32 s5, s17, s5
	v_mfma_f32_16x16x32_bf16 v[4:7], v[44:47], v[24:27], v[4:7]
	v_add3_u32 v46, s18, v36, v58
	v_add_u32_e32 v44, v60, v36
	s_ashr_i32 s29, s28, 31
	s_waitcnt lgkmcnt(2)
	v_mfma_f32_16x16x32_bf16 v[32:35], v[48:51], v[40:43], v[32:35]
	v_and_or_b32 v56, v76, 15, s0
	s_lshl_b64 s[0:1], s[28:29], 2
	s_add_u32 s0, s4, s0
	s_waitcnt lgkmcnt(0)
	v_mfma_f32_16x16x32_bf16 v[8:11], v[52:55], v[40:43], v[8:11]
	ds_read_b64_tr_b16 v[38:39], v57 offset:44608
	ds_read_b64_tr_b16 v[36:37], v57 offset:43520
	ds_read_b64_tr_b16 v[40:41], v57 offset:43552
	ds_read_b64_tr_b16 v[42:43], v57 offset:44640
	s_addc_u32 s1, s5, s1
	v_mfma_f32_16x16x32_bf16 v[16:19], v[48:51], v[24:27], v[16:19]
	v_mfma_f32_16x16x32_bf16 v[12:15], v[52:55], v[24:27], v[12:15]
	ds_read_b64_tr_b16 v[24:25], v44
	ds_read_b64_tr_b16 v[26:27], v44 offset:1088
	ds_read_b64_tr_b16 v[44:45], v46 offset:32
	ds_read_b64_tr_b16 v[46:47], v46 offset:1120
	ds_read_b64_tr_b16 v[48:49], v57 offset:43584
	ds_read_b64_tr_b16 v[50:51], v57 offset:44672
	ds_read_b64_tr_b16 v[52:53], v59 offset:43520
	ds_read_b64_tr_b16 v[54:55], v59 offset:44608
	s_waitcnt lgkmcnt(6)
	v_mfma_f32_16x16x32_bf16 v[20:23], v[36:39], v[24:27], v[20:23]
	v_mfma_f32_16x16x32_bf16 v[28:31], v[40:43], v[24:27], v[28:31]
	s_waitcnt lgkmcnt(2)
	v_mfma_f32_16x16x32_bf16 v[32:35], v[48:51], v[24:27], v[32:35]
	s_waitcnt lgkmcnt(0)
	v_mfma_f32_16x16x32_bf16 v[8:11], v[52:55], v[24:27], v[8:11]
	v_lshl_add_u64 v[24:25], s[0:1], 0, v[144:145]
	v_lshlrev_b32_e32 v144, 9, v56
	v_lshl_add_u64 v[24:25], v[24:25], 0, v[144:145]
	v_add_co_u32_e32 v26, vcc, 0x2000, v24
	v_mfma_f32_16x16x32_bf16 v[0:3], v[36:39], v[44:47], v[0:3]
	s_nop 0
	v_addc_co_u32_e32 v27, vcc, 0, v25, vcc
	s_mov_b64 s[0:1], 0
	v_mfma_f32_16x16x32_bf16 v[4:7], v[40:43], v[44:47], v[4:7]
	v_mfma_f32_16x16x32_bf16 v[16:19], v[48:51], v[44:47], v[16:19]
	v_mfma_f32_16x16x32_bf16 v[12:15], v[52:55], v[44:47], v[12:15]
	global_store_dwordx4 v[24:25], v[20:23], off
	global_store_dwordx4 v[24:25], v[28:31], off offset:64
	global_store_dwordx4 v[24:25], v[32:35], off offset:128
	global_store_dwordx4 v[24:25], v[8:11], off offset:192
	global_store_dwordx4 v[26:27], v[0:3], off
	s_nop 0
	global_store_dwordx4 v[26:27], v[4:7], off offset:64
	global_store_dwordx4 v[26:27], v[16:19], off offset:128
	global_store_dwordx4 v[26:27], v[12:15], off offset:192
	s_barrier

; #define LAS __attribute__((address_space(3)))
; __device__ __forceinline__ unsigned pk2(float lo, float hi) { return pg8::cvt_pk_bf16(lo, hi); }
; #define MFMA16(X, Y, ACC) ACC = __builtin_amdgcn_mfma_f32_16x16x32_bf16(X, Y, ACC, 0, 0, 0)
; __device__ __forceinline__ void ret_out(const Args& a, int tile, LAS unsigned char* lds, int tid, int lane, int wave) {
;     ...
;         u32x2 gr[4];
; #pragma unroll
;         for (int et = 0; et < 4; ++et) gr[et] = *(const u32x2*)(Z + (size_t)(t0 + cb * 16 + fr) * IW + 1792 + h * 128 + hv * 64 + et * 16 + 4 * fq);
;         if (hv == 0 || half) {
;             f32x4 sc[4];
; #pragma unroll
;             for (int mt = 0; mt < 4; ++mt) sc[mt] = (f32x4){0.f, 0.f, 0.f, 0.f};
; #pragma unroll
;             for (int ks = 0; ks < 4; ++ks) {
;                 const bf16x8 qf = *(const LAS bf16x8*)(lds + OFF_QS + ((cb * 16 + fr) * 136 + 32 * ks + 8 * fq) * 2);
; #pragma unroll
;                 for (int mt = 0; mt < 4; ++mt) { const bf16x8 kf = *(const LAS bf16x8*)(lds + OFF_KS + ((hv * 64 + mt * 16 + fr) * 136 + 32 * ks + 8 * fq) * 2); MFMA16(kf, qf, sc[mt]); }
;             }
; #pragma unroll
;             for (int mt = 0; mt < 4; ++mt) { const int m0 = hv * 64 + mt * 16 + 4 * fq; float v[4];
; #pragma unroll
;                 for (int r = 0; r < 4; ++r) { const int dm = cg - (m0 + r); v[r] = (dm >= 0) ? sc[mt][r] * __builtin_amdgcn_exp2f((float)dm * lg2) : 0.f; }
;                 u32x2 w; w.x = pk2(v[0], v[1]); w.y = pk2(v[2], v[3]);
;                 *(LAS u32x2*)(lds + OFF_SS + ((cb * 16 + fr) * 136 + m0) * 2) = w; }
;         }
.LBB0_1460:
	v_ldexp_f32 v56, v56, s0
	v_log_f32_e32 v56, v56
	v_cndmask_b32_e64 v57, 0, v193, s[74:75]
	s_andn2_b64 vcc, exec, s[4:5]
	v_add_u32_e32 v204, 0, v133
	v_sub_f32_e32 v114, v56, v57
	v_lshl_add_u64 v[56:57], s[34:35], 1, v[96:97]
	global_load_dwordx2 v[122:123], v[56:57], off offset:3584
	global_load_dwordx2 v[120:121], v[56:57], off offset:3616
	global_load_dwordx2 v[118:119], v[56:57], off offset:3648
	global_load_dwordx2 v[116:117], v[56:57], off offset:3680
	s_cbranch_vccnz .LBB0_1462
	ds_read_b128 v[186:189], v134 offset:17408
	ds_read_b128 v[214:217], v135 offset:17408
	ds_read_b128 v[218:221], v136 offset:17408
	ds_read_b128 v[222:225], v137 offset:17408
	ds_read_b128 v[226:229], v204
	ds_read_b128 v[230:233], v138 offset:17408
	ds_read_b128 v[234:237], v204 offset:64
	ds_read_b128 v[238:241], v139 offset:17408
	ds_read_b128 v[242:245], v140 offset:17408
	ds_read_b128 v[246:249], v141 offset:17408
	v_add_u32_e32 v60, 0, v134
	v_add_u32_e32 v64, 0, v135
	v_add_u32_e32 v68, 0, v136
	v_add_u32_e32 v72, 0, v137
	v_add_u32_e32 v76, 0, v138
	s_waitcnt lgkmcnt(5)
	v_mfma_f32_16x16x32_bf16 v[60:63], v[186:189], v[226:229], 0
	ds_read_b128 v[186:189], v204 offset:128
	v_mfma_f32_16x16x32_bf16 v[64:67], v[214:217], v[226:229], 0
	ds_read_b128 v[214:217], v142 offset:17408
	v_mfma_f32_16x16x32_bf16 v[68:71], v[218:221], v[226:229], 0
	ds_read_b128 v[218:221], v143 offset:17408
	v_mfma_f32_16x16x32_bf16 v[56:59], v[222:225], v[226:229], 0
	ds_read_b128 v[222:225], v150 offset:17408
	ds_read_b128 v[226:229], v151 offset:17408
	s_waitcnt lgkmcnt(8)
	v_mfma_f32_16x16x32_bf16 v[60:63], v[230:233], v[234:237], v[60:63]
	ds_read_b128 v[230:233], v152 offset:17408
	v_add_u32_e32 v76, 0, v139
	s_waitcnt lgkmcnt(8)
	v_mfma_f32_16x16x32_bf16 v[64:67], v[238:241], v[234:237], v[64:67]
	ds_read_b128 v[238:241], v153 offset:17408
	v_add_u32_e32 v76, 0, v140
	s_waitcnt lgkmcnt(8)
	v_mfma_f32_16x16x32_bf16 v[68:71], v[242:245], v[234:237], v[68:71]
	ds_read_b128 v[242:245], v154 offset:17408
	v_add_u32_e32 v76, 0, v141
	s_waitcnt lgkmcnt(8)
	v_mfma_f32_16x16x32_bf16 v[56:59], v[246:249], v[234:237], v[56:59]
	v_add_u32_e32 v76, 0, v142
	s_waitcnt lgkmcnt(6)
	v_mfma_f32_16x16x32_bf16 v[60:63], v[214:217], v[186:189], v[60:63]
	v_add_u32_e32 v76, 0, v143
	s_waitcnt lgkmcnt(5)
	v_mfma_f32_16x16x32_bf16 v[64:67], v[218:221], v[186:189], v[64:67]
	v_add_u32_e32 v76, 0, v150
	s_waitcnt lgkmcnt(4)
	v_mfma_f32_16x16x32_bf16 v[68:71], v[222:225], v[186:189], v[68:71]
	v_add_u32_e32 v76, 0, v151
	s_waitcnt lgkmcnt(3)
	v_mfma_f32_16x16x32_bf16 v[56:59], v[226:229], v[186:189], v[56:59]
	v_add_u32_e32 v76, 0, v152
	ds_read_b128 v[72:75], v204 offset:192
	s_waitcnt lgkmcnt(0)
	v_mfma_f32_16x16x32_bf16 v[60:63], v[230:233], v[72:75], v[60:63]
	v_add_u32_e32 v76, 0, v153
	s_waitcnt lgkmcnt(0)
	v_mfma_f32_16x16x32_bf16 v[64:67], v[238:241], v[72:75], v[64:67]
	v_add_u32_e32 v76, 0, v154
	s_waitcnt lgkmcnt(0)
	v_mfma_f32_16x16x32_bf16 v[68:71], v[242:245], v[72:75], v[68:71]
	v_add_u32_e32 v76, 0, v155
	ds_read_b128 v[76:79], v155 offset:17408
	s_waitcnt lgkmcnt(0)
	v_mfma_f32_16x16x32_bf16 v[56:59], v[76:79], v[72:75], v[56:59]
	v_mul_f32_e32 v72, v114, v156
	v_exp_f32_e32 v72, v72
	s_nop 0
	v_mul_f32_e32 v60, v72, v60
	v_mul_f32_e32 v72, v114, v157
	v_exp_f32_e32 v72, v72
	v_cndmask_b32_e64 v60, 0, v60, s[42:43]
	v_mul_f32_e32 v61, v72, v61
	v_mul_f32_e32 v72, v114, v158
	v_exp_f32_e32 v72, v72
	v_cndmask_b32_e64 v61, 0, v61, s[44:45]
	v_cvt_pk_bf16_f32 v60, v60, v61
	v_mul_f32_e32 v62, v72, v62
	v_mul_f32_e32 v72, v114, v159
	v_exp_f32_e32 v72, v72
	v_cndmask_b32_e64 v62, 0, v62, s[46:47]
	v_mul_f32_e32 v63, v72, v63
	v_cndmask_b32_e64 v63, 0, v63, s[48:49]
	v_cvt_pk_bf16_f32 v61, v62, v63
	ds_write_b64 v200, v[60:61]
	v_mul_f32_e32 v60, v114, v160
	v_exp_f32_e32 v60, v60
	v_mul_f32_e32 v61, v114, v161
	v_exp_f32_e32 v61, v61
	v_mul_f32_e32 v62, v114, v162
	v_mul_f32_e32 v63, v114, v163
	v_exp_f32_e32 v62, v62
	v_exp_f32_e32 v63, v63
	v_mul_f32_e32 v60, v60, v64
	v_cndmask_b32_e64 v60, 0, v60, s[50:51]
	v_mul_f32_e32 v61, v61, v65
	v_cndmask_b32_e64 v61, 0, v61, s[52:53]
	v_mul_f32_e32 v62, v62, v66
	v_mul_f32_e32 v63, v63, v67
	v_cvt_pk_bf16_f32 v60, v60, v61
	v_cndmask_b32_e64 v62, 0, v62, s[54:55]
	v_cndmask_b32_e64 v63, 0, v63, s[56:57]
	v_cvt_pk_bf16_f32 v61, v62, v63
	ds_write_b64 v201, v[60:61]
	v_mul_f32_e32 v60, v114, v164
	v_exp_f32_e32 v60, v60
	v_mul_f32_e32 v61, v114, v165
	v_exp_f32_e32 v61, v61
	v_mul_f32_e32 v62, v114, v166
	v_mul_f32_e32 v63, v114, v167
	v_exp_f32_e32 v62, v62
	v_exp_f32_e32 v63, v63
	v_mul_f32_e32 v60, v60, v68
	v_cndmask_b32_e64 v60, 0, v60, s[58:59]
	v_mul_f32_e32 v61, v61, v69
	v_cndmask_b32_e64 v61, 0, v61, s[60:61]
	v_mul_f32_e32 v62, v62, v70
	v_mul_f32_e32 v63, v63, v71
	v_cvt_pk_bf16_f32 v60, v60, v61
	v_cndmask_b32_e64 v62, 0, v62, s[62:63]
	v_cndmask_b32_e64 v63, 0, v63, s[64:65]
	v_cvt_pk_bf16_f32 v61, v62, v63
	ds_write_b64 v202, v[60:61]
	v_mul_f32_e32 v60, v114, v168
	v_exp_f32_e32 v60, v60
	s_nop 0
	v_mul_f32_e32 v56, v60, v56
	v_mul_f32_e32 v60, v114, v169
	v_exp_f32_e32 v60, v60
	v_cndmask_b32_e64 v56, 0, v56, s[66:67]
	v_mul_f32_e32 v57, v60, v57
	v_mul_f32_e32 v60, v114, v170
	v_exp_f32_e32 v60, v60
	v_cndmask_b32_e64 v57, 0, v57, s[68:69]
	v_cvt_pk_bf16_f32 v56, v56, v57
	v_mul_f32_e32 v58, v60, v58
	v_mul_f32_e32 v60, v114, v171
	v_exp_f32_e32 v60, v60
	v_cndmask_b32_e64 v58, 0, v58, s[70:71]
	v_mul_f32_e32 v59, v60, v59
	v_cndmask_b32_e64 v59, 0, v59, s[72:73]
	v_cvt_pk_bf16_f32 v57, v58, v59
	ds_write_b64 v203, v[56:57]
; #define LAS __attribute__((address_space(3)))
; #define MFMA16(X, Y, ACC) ACC = __builtin_amdgcn_mfma_f32_16x16x32_bf16(X, Y, ACC, 0, 0, 0)
; __device__ __forceinline__ void ret_out(const Args& a, int tile, LAS unsigned char* lds, int tid, int lane, int wave) {
;     ...
;         __syncthreads();
;         f32x4 oi[4], oc[4];
; #pragma unroll
;         for (int et = 0; et < 4; ++et) { oi[et] = (f32x4){0.f, 0.f, 0.f, 0.f}; oc[et] = (f32x4){0.f, 0.f, 0.f, 0.f}; }
; #pragma unroll
;         for (int ks = 0; ks < 4; ++ks) {
;             const bf16x8 qf = *(const LAS bf16x8*)(lds + OFF_QS + ((cb * 16 + fr) * 136 + 32 * ks + 8 * fq) * 2);
; #pragma unroll
;             for (int et = 0; et < 4; ++et) { const bf16x8 pf = *(const LAS bf16x8*)(lds + OFF_PT + ((hv * 64 + et * 16 + fr) * 136 + 32 * ks + 8 * fq) * 2); MFMA16(pf, qf, oc[et]); }
;             if (ks < nit) {
;                 const bf16x8 sf = *(const LAS bf16x8*)(lds + OFF_SS + ((cb * 16 + fr) * 136 + 32 * ks + 8 * fq) * 2);
; #pragma unroll
;                 for (int et = 0; et < 4; ++et) { const bf16x8 vf = tr_frag(lds + OFF_VT, 272, 32 * ks, hv * 64 + et * 16, lane); MFMA16(vf, sf, oi[et]); }
;             }
;         }
.LBB0_1462:
	v_add_u32_e32 v60, s97, v134
	s_waitcnt lgkmcnt(0)
	s_barrier
	ds_read_b128 v[56:59], v204
	ds_read_b128 v[60:63], v60
	ds_read_b64_tr_b16 v[80:81], v172 offset:52320
	ds_read_b64_tr_b16 v[82:83], v172 offset:53408
	ds_read_b128 v[210:213], v204 offset:64
	v_add_u32_e32 v184, 0x1dc00, v204
	ds_read_b128 v[186:189], v184
	ds_read_b128 v[214:217], v184 offset:64
	s_and_b64 vcc, exec, s[38:39]
	v_add_u32_e32 v205, s96, v133
	s_waitcnt lgkmcnt(5)
	v_mfma_f32_16x16x32_bf16 v[72:75], v[60:63], v[56:59], 0
	v_add_u32_e32 v60, s97, v135
	ds_read_b128 v[60:63], v60
	s_waitcnt lgkmcnt(0)
	v_mfma_f32_16x16x32_bf16 v[76:79], v[60:63], v[56:59], 0
	v_add_u32_e32 v60, s97, v136
	ds_read_b128 v[60:63], v60
	s_waitcnt lgkmcnt(0)
	v_mfma_f32_16x16x32_bf16 v[180:183], v[60:63], v[56:59], 0
	v_add_u32_e32 v60, s97, v137
	ds_read_b128 v[60:63], v60
	s_waitcnt lgkmcnt(0)
	v_mfma_f32_16x16x32_bf16 v[206:209], v[60:63], v[56:59], 0
	ds_read_b64_tr_b16 v[58:59], v172 offset:53312
	ds_read_b64_tr_b16 v[56:57], v172 offset:52224
	ds_read_b64_tr_b16 v[60:61], v172 offset:52256
	ds_read_b64_tr_b16 v[62:63], v172 offset:53344
	s_waitcnt lgkmcnt(0)
	v_mfma_f32_16x16x32_bf16 v[64:67], v[60:63], v[186:189], 0
	ds_read_b64_tr_b16 v[60:61], v172 offset:52288
	ds_read_b64_tr_b16 v[62:63], v172 offset:53376
	v_mfma_f32_16x16x32_bf16 v[56:59], v[56:59], v[186:189], 0
	s_waitcnt lgkmcnt(0)
	v_mfma_f32_16x16x32_bf16 v[60:63], v[60:63], v[186:189], 0
	s_waitcnt lgkmcnt(0)
	v_mfma_f32_16x16x32_bf16 v[68:71], v[80:83], v[186:189], 0
	v_add_u32_e32 v80, s97, v138
	ds_read_b128 v[80:83], v80
	s_waitcnt lgkmcnt(0)
	v_mfma_f32_16x16x32_bf16 v[84:87], v[80:83], v[210:213], v[72:75]
	s_nop 2
	v_add_u32_e32 v72, s97, v139
	ds_read_b128 v[72:75], v72
	s_waitcnt lgkmcnt(0)
	v_mfma_f32_16x16x32_bf16 v[80:83], v[72:75], v[210:213], v[76:79]
	v_add_u32_e32 v72, s97, v140
	ds_read_b128 v[72:75], v72
	s_waitcnt lgkmcnt(0)
	v_mfma_f32_16x16x32_bf16 v[76:79], v[72:75], v[210:213], v[180:183]
	v_add_u32_e32 v72, s97, v141
	ds_read_b128 v[72:75], v72
	s_waitcnt lgkmcnt(0)
	v_mfma_f32_16x16x32_bf16 v[72:75], v[72:75], v[210:213], v[206:209]
	s_nop 1
	ds_read_b64_tr_b16 v[206:207], v172 offset:60928
	ds_read_b64_tr_b16 v[208:209], v172 offset:62016
	v_add_u32_e32 v184, s97, v142
	ds_read_b128 v[186:189], v184
	s_waitcnt lgkmcnt(1)
	v_mfma_f32_16x16x32_bf16 v[56:59], v[206:209], v[214:217], v[56:59]
	ds_read_b64_tr_b16 v[206:207], v172 offset:60960
	ds_read_b64_tr_b16 v[208:209], v172 offset:62048
	s_waitcnt lgkmcnt(0)
	v_mfma_f32_16x16x32_bf16 v[64:67], v[206:209], v[214:217], v[64:67]
	ds_read_b64_tr_b16 v[206:207], v172 offset:60992
	ds_read_b64_tr_b16 v[208:209], v172 offset:62080
	s_waitcnt lgkmcnt(0)
	v_mfma_f32_16x16x32_bf16 v[60:63], v[206:209], v[214:217], v[60:63]
	ds_read_b64_tr_b16 v[206:207], v172 offset:61024
	ds_read_b64_tr_b16 v[208:209], v172 offset:62112
	s_waitcnt lgkmcnt(0)
	v_mfma_f32_16x16x32_bf16 v[68:71], v[206:209], v[214:217], v[68:71]
	ds_read_b128 v[180:183], v204 offset:128
	v_add_u32_e32 v184, s97, v143
	ds_read_b128 v[214:217], v184
	s_waitcnt lgkmcnt(1)
	v_mfma_f32_16x16x32_bf16 v[84:87], v[186:189], v[180:183], v[84:87]
	v_add_u32_e32 v184, s97, v150
	ds_read_b128 v[186:189], v184
	s_waitcnt lgkmcnt(1)
	v_mfma_f32_16x16x32_bf16 v[80:83], v[214:217], v[180:183], v[80:83]
	v_add_u32_e32 v184, s97, v151
	s_waitcnt lgkmcnt(0)
	v_mfma_f32_16x16x32_bf16 v[76:79], v[186:189], v[180:183], v[76:79]
	ds_read_b128 v[206:209], v184
	s_waitcnt lgkmcnt(0)
	v_mfma_f32_16x16x32_bf16 v[72:75], v[206:209], v[180:183], v[72:75]
	s_cbranch_vccnz .LBB0_1464
	ds_read_b128 v[180:183], v205 offset:128
	ds_read_b64_tr_b16 v[208:209], v173 offset:18496
	ds_read_b64_tr_b16 v[206:207], v173 offset:17408
	ds_read_b64_tr_b16 v[210:211], v173 offset:17440
	ds_read_b64_tr_b16 v[212:213], v173 offset:18528
	s_waitcnt lgkmcnt(2)
	v_mfma_f32_16x16x32_bf16 v[56:59], v[206:209], v[180:183], v[56:59]
	ds_read_b64_tr_b16 v[206:207], v173 offset:17472
	ds_read_b64_tr_b16 v[208:209], v173 offset:18560
	s_waitcnt lgkmcnt(0)
	v_mfma_f32_16x16x32_bf16 v[60:63], v[206:209], v[180:183], v[60:63]
	ds_read_b64_tr_b16 v[206:207], v173 offset:17504
	ds_read_b64_tr_b16 v[208:209], v173 offset:18592
	v_mfma_f32_16x16x32_bf16 v[64:67], v[210:213], v[180:183], v[64:67]
	s_waitcnt lgkmcnt(0)
	v_mfma_f32_16x16x32_bf16 v[68:71], v[206:209], v[180:183], v[68:71]
.LBB0_1464:
	ds_read_b128 v[180:183], v204 offset:192
	v_add_u32_e32 v184, s97, v152
	ds_read_b128 v[186:189], v184
	v_add_u32_e32 v184, s97, v153
	ds_read_b128 v[214:217], v184
	s_and_b64 vcc, exec, s[38:39]
	s_waitcnt lgkmcnt(1)
	v_mfma_f32_16x16x32_bf16 v[84:87], v[186:189], v[180:183], v[84:87]
	v_add_u32_e32 v184, s97, v154
	ds_read_b128 v[186:189], v184
	s_waitcnt lgkmcnt(1)
	v_mfma_f32_16x16x32_bf16 v[80:83], v[214:217], v[180:183], v[80:83]
	v_add_u32_e32 v184, s97, v155
	s_waitcnt lgkmcnt(0)
	v_mfma_f32_16x16x32_bf16 v[76:79], v[186:189], v[180:183], v[76:79]
	ds_read_b128 v[206:209], v184
	s_waitcnt lgkmcnt(0)
	v_mfma_f32_16x16x32_bf16 v[72:75], v[206:209], v[180:183], v[72:75]
	s_cbranch_vccnz .LBB0_1466
	ds_read_b128 v[180:183], v205 offset:192
	ds_read_b64_tr_b16 v[206:207], v173 offset:27200
	ds_read_b64_tr_b16 v[208:209], v173 offset:26144
	ds_read_b64_tr_b16 v[210:211], v173 offset:27232
	ds_read_b64_tr_b16 v[204:205], v173 offset:26112
	s_waitcnt lgkmcnt(0)
	v_mfma_f32_16x16x32_bf16 v[56:59], v[204:207], v[180:183], v[56:59]
	ds_read_b64_tr_b16 v[204:205], v173 offset:26176
	ds_read_b64_tr_b16 v[206:207], v173 offset:27264
	s_waitcnt lgkmcnt(0)
	v_mfma_f32_16x16x32_bf16 v[60:63], v[204:207], v[180:183], v[60:63]
	ds_read_b64_tr_b16 v[204:205], v173 offset:26208
	ds_read_b64_tr_b16 v[206:207], v173 offset:27296
	v_mfma_f32_16x16x32_bf16 v[64:67], v[208:211], v[180:183], v[64:67]
	s_waitcnt lgkmcnt(0)
	v_mfma_f32_16x16x32_bf16 v[68:71], v[204:207], v[180:183], v[68:71]

; #define LAS __attribute__((address_space(3)))
; #define MFMA16(X, Y, ACC) ACC = __builtin_amdgcn_mfma_f32_16x16x32_bf16(X, Y, ACC, 0, 0, 0)
; __device__ __forceinline__ void s5_m3(const Args& a, int l, int tile, LAS unsigned char* lds, int tid, int lane, int wave) {
;     ...
;         const int cb = wave & 3, jh = wave >> 2; const bf16* WG = (const bf16*)(wl + WL_GLU);
;         f32x4 acc[8];
; #pragma unroll
;         for (int jt = 0; jt < 8; ++jt) acc[jt] = (f32x4){0.f, 0.f, 0.f, 0.f};
; #pragma unroll
;         for (int ks = 0; ks < 8; ++ks) {
;             const bf16x8 yv = *(const LAS bf16x8*)(lds + OFF_YS + ((cb * 16 + fr) * 264 + 32 * ks + 8 * fq) * 2);
; #pragma unroll
;             for (int jt = 0; jt < 8; ++jt) { const bf16x8 wv = *(const bf16x8*)(WG + (size_t)(jh * 128 + jt * 16 + fr) * 256 + 32 * ks + 8 * fq); MFMA16(wv, yv, acc[jt]); }
;         }
.LBB0_1498:
	s_ashr_i32 s4, s29, 8
	s_lshl_b32 s0, s28, 4
	v_and_or_b32 v36, s0, 48, v71
	s_lshl_b32 s0, s4, 7
	v_or_b32_e32 v30, s0, v71
	v_readlane_b32 s6, v254, 57
	v_lshlrev_b32_e32 v144, 1, v70
	v_readlane_b32 s7, v254, 58
	v_ashrrev_i32_e32 v31, 31, v30
	s_movk_i32 s1, 0x108
	v_lshl_add_u64 v[54:55], s[6:7], 0, v[144:145]
	v_lshlrev_b64 v[0:1], 9, v[30:31]
	v_mad_u32_u24 v2, v36, s1, v70
	v_lshl_add_u64 v[0:1], v[54:55], 0, v[0:1]
	s_waitcnt lgkmcnt(0)
	s_barrier
	v_lshl_add_u32 v12, v2, 1, s3
	v_mov_b32_e32 v190, 0x2000
	v_mov_b32_e32 v191, 0
	global_load_dwordx4 v[198:201], v[0:1], off
	v_lshl_add_u64 v[2:3], v[0:1], 0, v[190:191]
	global_load_dwordx4 v[202:205], v[2:3], off
	v_lshl_add_u64 v[4:5], v[2:3], 0, v[190:191]
	global_load_dwordx4 v[206:209], v[4:5], off
	v_lshl_add_u64 v[6:7], v[4:5], 0, v[190:191]
	global_load_dwordx4 v[210:213], v[6:7], off
	v_lshl_add_u64 v[8:9], v[6:7], 0, v[190:191]
	global_load_dwordx4 v[214:217], v[8:9], off
	v_lshl_add_u64 v[10:11], v[8:9], 0, v[190:191]
	global_load_dwordx4 v[218:221], v[10:11], off
	v_lshl_add_u64 v[28:29], v[10:11], 0, v[190:191]
	global_load_dwordx4 v[222:225], v[28:29], off
	v_lshl_add_u64 v[30:31], v[28:29], 0, v[190:191]
	global_load_dwordx4 v[226:229], v[30:31], off
	ds_read_b128 v[162:165], v12
	ds_read_b128 v[166:169], v12 offset:64
	v_readlane_b32 s6, v254, 59
	v_readlane_b32 s7, v254, 60
	v_cmp_gt_u32_e32 vcc, 16, v69
	global_load_dwordx4 v[230:233], v[0:1], off offset:64
	global_load_dwordx4 v[234:237], v[2:3], off offset:64
	global_load_dwordx4 v[238:241], v[4:5], off offset:64
	global_load_dwordx4 v[242:245], v[6:7], off offset:64
	global_load_dwordx4 v[246:249], v[8:9], off offset:64
	global_load_dwordx4 v[150:153], v[10:11], off offset:64
	global_load_dwordx4 v[154:157], v[28:29], off offset:64
	global_load_dwordx4 v[158:161], v[30:31], off offset:64
	s_waitcnt vmcnt(15) lgkmcnt(1)
	v_mfma_f32_16x16x32_bf16 v[18:21], v[198:201], v[162:165], 0
	global_load_dwordx4 v[198:201], v[0:1], off offset:128
	s_waitcnt vmcnt(15)
	v_mfma_f32_16x16x32_bf16 v[22:25], v[202:205], v[162:165], 0
	global_load_dwordx4 v[202:205], v[2:3], off offset:128
	s_waitcnt vmcnt(15)
	v_mfma_f32_16x16x32_bf16 v[32:35], v[206:209], v[162:165], 0
	global_load_dwordx4 v[206:209], v[4:5], off offset:128
	s_waitcnt vmcnt(15)
	v_mfma_f32_16x16x32_bf16 v[38:41], v[210:213], v[162:165], 0
	global_load_dwordx4 v[210:213], v[6:7], off offset:128
	s_waitcnt vmcnt(15)
	v_mfma_f32_16x16x32_bf16 v[42:45], v[214:217], v[162:165], 0
	global_load_dwordx4 v[214:217], v[8:9], off offset:128
	s_waitcnt vmcnt(15)
	v_mfma_f32_16x16x32_bf16 v[46:49], v[218:221], v[162:165], 0
	global_load_dwordx4 v[218:221], v[10:11], off offset:128
	s_waitcnt vmcnt(15)
	v_mfma_f32_16x16x32_bf16 v[50:53], v[222:225], v[162:165], 0
	global_load_dwordx4 v[222:225], v[28:29], off offset:128
	s_waitcnt vmcnt(15)
	v_mfma_f32_16x16x32_bf16 v[14:17], v[226:229], v[162:165], 0
	global_load_dwordx4 v[226:229], v[30:31], off offset:128
	ds_read_b128 v[162:165], v12 offset:128
	s_waitcnt vmcnt(15) lgkmcnt(1)
	v_mfma_f32_16x16x32_bf16 v[18:21], v[230:233], v[166:169], v[18:21]
	global_load_dwordx4 v[230:233], v[0:1], off offset:192
	s_waitcnt vmcnt(15)
	v_mfma_f32_16x16x32_bf16 v[22:25], v[234:237], v[166:169], v[22:25]
	global_load_dwordx4 v[234:237], v[2:3], off offset:192
	s_waitcnt vmcnt(15)
	v_mfma_f32_16x16x32_bf16 v[32:35], v[238:241], v[166:169], v[32:35]
	global_load_dwordx4 v[238:241], v[4:5], off offset:192
	s_waitcnt vmcnt(15)
	v_mfma_f32_16x16x32_bf16 v[38:41], v[242:245], v[166:169], v[38:41]
	global_load_dwordx4 v[242:245], v[6:7], off offset:192
	s_waitcnt vmcnt(15)
	v_mfma_f32_16x16x32_bf16 v[42:45], v[246:249], v[166:169], v[42:45]
	global_load_dwordx4 v[246:249], v[8:9], off offset:192
	s_waitcnt vmcnt(15)
	v_mfma_f32_16x16x32_bf16 v[46:49], v[150:153], v[166:169], v[46:49]
	global_load_dwordx4 v[150:153], v[10:11], off offset:192
	s_waitcnt vmcnt(15)
	v_mfma_f32_16x16x32_bf16 v[50:53], v[154:157], v[166:169], v[50:53]
	global_load_dwordx4 v[154:157], v[28:29], off offset:192
	s_waitcnt vmcnt(15)
	v_mfma_f32_16x16x32_bf16 v[14:17], v[158:161], v[166:169], v[14:17]
	global_load_dwordx4 v[158:161], v[30:31], off offset:192
	ds_read_b128 v[166:169], v12 offset:192
	s_waitcnt vmcnt(15) lgkmcnt(1)
	v_mfma_f32_16x16x32_bf16 v[18:21], v[198:201], v[162:165], v[18:21]
	global_load_dwordx4 v[198:201], v[0:1], off offset:256
	s_waitcnt vmcnt(15)
	v_mfma_f32_16x16x32_bf16 v[22:25], v[202:205], v[162:165], v[22:25]
	global_load_dwordx4 v[202:205], v[2:3], off offset:256
	s_waitcnt vmcnt(15)
	v_mfma_f32_16x16x32_bf16 v[32:35], v[206:209], v[162:165], v[32:35]
	global_load_dwordx4 v[206:209], v[4:5], off offset:256
	s_waitcnt vmcnt(15)
	v_mfma_f32_16x16x32_bf16 v[38:41], v[210:213], v[162:165], v[38:41]
	global_load_dwordx4 v[210:213], v[6:7], off offset:256
	s_waitcnt vmcnt(15)
	v_mfma_f32_16x16x32_bf16 v[42:45], v[214:217], v[162:165], v[42:45]
	global_load_dwordx4 v[214:217], v[8:9], off offset:256
	s_waitcnt vmcnt(15)
	v_mfma_f32_16x16x32_bf16 v[46:49], v[218:221], v[162:165], v[46:49]
	global_load_dwordx4 v[218:221], v[10:11], off offset:256
	s_waitcnt vmcnt(15)
	v_mfma_f32_16x16x32_bf16 v[50:53], v[222:225], v[162:165], v[50:53]
	global_load_dwordx4 v[222:225], v[28:29], off offset:256
	s_waitcnt vmcnt(15)
	v_mfma_f32_16x16x32_bf16 v[14:17], v[226:229], v[162:165], v[14:17]
	global_load_dwordx4 v[226:229], v[30:31], off offset:256
	ds_read_b128 v[162:165], v12 offset:256
	s_waitcnt vmcnt(15) lgkmcnt(1)
	v_mfma_f32_16x16x32_bf16 v[18:21], v[230:233], v[166:169], v[18:21]
	global_load_dwordx4 v[230:233], v[0:1], off offset:320
	s_waitcnt vmcnt(15)
; #define LAS __attribute__((address_space(3)))
; __device__ __forceinline__ float sigmoidf_(float x) { return __builtin_amdgcn_rcpf(1.0f + __expf(-x)); }
; #define MFMA16(X, Y, ACC) ACC = __builtin_amdgcn_mfma_f32_16x16x32_bf16(X, Y, ACC, 0, 0, 0)
; __device__ __forceinline__ void s5_m3(const Args& a, int l, int tile, LAS unsigned char* lds, int tid, int lane, int wave) {
;     ...
;         for (int ks = 0; ks < 8; ++ks) {
;             const bf16x8 yv = *(const LAS bf16x8*)(lds + OFF_YS + ((cb * 16 + fr) * 264 + 32 * ks + 8 * fq) * 2);
; #pragma unroll
;             for (int jt = 0; jt < 8; ++jt) { const bf16x8 wv = *(const bf16x8*)(WG + (size_t)(jh * 128 + jt * 16 + fr) * 256 + 32 * ks + 8 * fq); MFMA16(wv, yv, acc[jt]); }
;         }
;         const int t = cb * 16 + fr; float ss = 0.f;
; #pragma unroll
;         for (int jt = 0; jt < 8; ++jt) {
;             const int j0 = jh * 128 + jt * 16 + 4 * fq;
;             const f32x4 bg = *(const f32x4*)(a.in[16] + (size_t)l * 256 + j0);
;             const u32x2 yr = *(const LAS u32x2*)(lds + OFF_YS + (t * 264 + j0) * 2);
;             f32x4 o;
;             o.x = __uint_as_float(yr.x << 16) * sigmoidf_(acc[jt].x + bg.x); o.y = __uint_as_float(yr.x & 0xffff0000u) * sigmoidf_(acc[jt].y + bg.y);
;             o.z = __uint_as_float(yr.y << 16) * sigmoidf_(acc[jt].z + bg.z); o.w = __uint_as_float(yr.y & 0xffff0000u) * sigmoidf_(acc[jt].w + bg.w);
;             acc[jt] = o; ss += (o.x * o.x + o.y * o.y) + (o.z * o.z + o.w * o.w);
	v_mfma_f32_16x16x32_bf16 v[22:25], v[234:237], v[166:169], v[22:25]
	global_load_dwordx4 v[234:237], v[2:3], off offset:320
	s_waitcnt vmcnt(15)
	v_mfma_f32_16x16x32_bf16 v[32:35], v[238:241], v[166:169], v[32:35]
	global_load_dwordx4 v[238:241], v[4:5], off offset:320
	s_waitcnt vmcnt(15)
	v_mfma_f32_16x16x32_bf16 v[38:41], v[242:245], v[166:169], v[38:41]
	global_load_dwordx4 v[242:245], v[6:7], off offset:320
	s_waitcnt vmcnt(15)
	v_mfma_f32_16x16x32_bf16 v[42:45], v[246:249], v[166:169], v[42:45]
	global_load_dwordx4 v[246:249], v[8:9], off offset:320
	s_waitcnt vmcnt(15)
	v_mfma_f32_16x16x32_bf16 v[46:49], v[150:153], v[166:169], v[46:49]
	global_load_dwordx4 v[150:153], v[10:11], off offset:320
	s_waitcnt vmcnt(15)
	v_mfma_f32_16x16x32_bf16 v[50:53], v[154:157], v[166:169], v[50:53]
	global_load_dwordx4 v[154:157], v[28:29], off offset:320
	s_waitcnt vmcnt(15)
	v_mfma_f32_16x16x32_bf16 v[14:17], v[158:161], v[166:169], v[14:17]
	global_load_dwordx4 v[158:161], v[30:31], off offset:320
	ds_read_b128 v[166:169], v12 offset:320
	s_waitcnt vmcnt(15) lgkmcnt(1)
	v_mfma_f32_16x16x32_bf16 v[18:21], v[198:201], v[162:165], v[18:21]
	global_load_dwordx4 v[198:201], v[0:1], off offset:384
	s_waitcnt vmcnt(15)
	v_mfma_f32_16x16x32_bf16 v[22:25], v[202:205], v[162:165], v[22:25]
	global_load_dwordx4 v[202:205], v[2:3], off offset:384
	s_waitcnt vmcnt(15)
	v_mfma_f32_16x16x32_bf16 v[32:35], v[206:209], v[162:165], v[32:35]
	global_load_dwordx4 v[206:209], v[4:5], off offset:384
	s_waitcnt vmcnt(15)
	v_mfma_f32_16x16x32_bf16 v[38:41], v[210:213], v[162:165], v[38:41]
	global_load_dwordx4 v[210:213], v[6:7], off offset:384
	s_waitcnt vmcnt(15)
	v_mfma_f32_16x16x32_bf16 v[42:45], v[214:217], v[162:165], v[42:45]
	global_load_dwordx4 v[214:217], v[8:9], off offset:384
	s_waitcnt vmcnt(15)
	v_mfma_f32_16x16x32_bf16 v[46:49], v[218:221], v[162:165], v[46:49]
	global_load_dwordx4 v[218:221], v[10:11], off offset:384
	s_waitcnt vmcnt(15)
	v_mfma_f32_16x16x32_bf16 v[50:53], v[222:225], v[162:165], v[50:53]
	global_load_dwordx4 v[222:225], v[28:29], off offset:384
	s_waitcnt vmcnt(15)
	v_mfma_f32_16x16x32_bf16 v[14:17], v[226:229], v[162:165], v[14:17]
	global_load_dwordx4 v[226:229], v[30:31], off offset:384
	ds_read_b128 v[162:165], v12 offset:384
	s_waitcnt vmcnt(15) lgkmcnt(1)
	v_mfma_f32_16x16x32_bf16 v[18:21], v[230:233], v[166:169], v[18:21]
	global_load_dwordx4 v[230:233], v[0:1], off offset:448
	s_waitcnt vmcnt(15)
	v_mfma_f32_16x16x32_bf16 v[22:25], v[234:237], v[166:169], v[22:25]
	global_load_dwordx4 v[234:237], v[2:3], off offset:448
	s_waitcnt vmcnt(15)
	v_mfma_f32_16x16x32_bf16 v[32:35], v[238:241], v[166:169], v[32:35]
	global_load_dwordx4 v[238:241], v[4:5], off offset:448
	s_waitcnt vmcnt(15)
	v_mfma_f32_16x16x32_bf16 v[38:41], v[242:245], v[166:169], v[38:41]
	global_load_dwordx4 v[242:245], v[6:7], off offset:448
	s_waitcnt vmcnt(15)
	v_mfma_f32_16x16x32_bf16 v[42:45], v[246:249], v[166:169], v[42:45]
	global_load_dwordx4 v[246:249], v[8:9], off offset:448
	s_waitcnt vmcnt(15)
	v_mfma_f32_16x16x32_bf16 v[46:49], v[150:153], v[166:169], v[46:49]
	global_load_dwordx4 v[150:153], v[10:11], off offset:448
	s_waitcnt vmcnt(15)
	v_mfma_f32_16x16x32_bf16 v[50:53], v[154:157], v[166:169], v[50:53]
	global_load_dwordx4 v[154:157], v[28:29], off offset:448
	s_waitcnt vmcnt(15)
	v_mfma_f32_16x16x32_bf16 v[14:17], v[158:161], v[166:169], v[14:17]
	global_load_dwordx4 v[158:161], v[30:31], off offset:448
	s_waitcnt vmcnt(15) lgkmcnt(0)
	v_mfma_f32_16x16x32_bf16 v[18:21], v[198:201], v[162:165], v[18:21]
	s_waitcnt vmcnt(14)
	v_mfma_f32_16x16x32_bf16 v[22:25], v[202:205], v[162:165], v[22:25]
	s_waitcnt vmcnt(13)
	v_mfma_f32_16x16x32_bf16 v[32:35], v[206:209], v[162:165], v[32:35]
	s_waitcnt vmcnt(12)
	v_mfma_f32_16x16x32_bf16 v[38:41], v[210:213], v[162:165], v[38:41]
	s_waitcnt vmcnt(11)
	v_mfma_f32_16x16x32_bf16 v[42:45], v[214:217], v[162:165], v[42:45]
	s_waitcnt vmcnt(10)
	v_mfma_f32_16x16x32_bf16 v[46:49], v[218:221], v[162:165], v[46:49]
	s_waitcnt vmcnt(9)
	v_mfma_f32_16x16x32_bf16 v[50:53], v[222:225], v[162:165], v[50:53]
	s_waitcnt vmcnt(8)
	v_mfma_f32_16x16x32_bf16 v[54:57], v[226:229], v[162:165], v[14:17]
	ds_read_b128 v[58:61], v12 offset:448
	s_nop 1
	s_nop 0
	s_waitcnt vmcnt(0) lgkmcnt(0)
	v_mfma_f32_16x16x32_bf16 v[24:27], v[234:237], v[58:61], v[22:25]
	v_mfma_f32_16x16x32_bf16 v[62:65], v[230:233], v[58:61], v[18:21]
	s_waitcnt vmcnt(0)
	v_mfma_f32_16x16x32_bf16 v[20:23], v[238:241], v[58:61], v[32:35]
	s_nop 1
	v_or_b32_e32 v32, s0, v68
	v_ashrrev_i32_e32 v33, 31, v32
	v_lshl_add_u64 v[34:35], v[32:33], 2, s[6:7]
	global_load_dwordx4 v[198:201], v[34:35], off
	global_load_dwordx4 v[202:205], v[34:35], off offset:64
	global_load_dwordx4 v[206:209], v[34:35], off offset:128
	global_load_dwordx4 v[210:213], v[34:35], off offset:192
	global_load_dwordx4 v[214:217], v[34:35], off offset:256
	global_load_dwordx4 v[218:221], v[34:35], off offset:320
	s_waitcnt vmcnt(6)
	v_mfma_f32_16x16x32_bf16 v[16:19], v[242:245], v[58:61], v[38:41]
	s_waitcnt vmcnt(6)
	v_mfma_f32_16x16x32_bf16 v[12:15], v[246:249], v[58:61], v[42:45]
	s_nop 1
	s_waitcnt vmcnt(5)
	v_add_f32_e32 v38, v62, v198
	v_mfma_f32_16x16x32_bf16 v[8:11], v[150:153], v[58:61], v[46:49]
	v_mul_f32_e32 v38, 0xbfb8aa3b, v38
	v_exp_f32_e32 v38, v38
	v_mad_u32_u24 v28, v36, s1, v32
	v_lshl_add_u32 v41, v28, 1, s3
	s_waitcnt vmcnt(5)
	v_mfma_f32_16x16x32_bf16 v[4:7], v[154:157], v[58:61], v[50:53]
	ds_read2_b64 v[28:31], v41 offset1:4
	v_add_f32_e32 v38, 1.0, v38
	v_rcp_f32_e32 v38, v38
	v_add_f32_e32 v39, v64, v200
	v_mul_f32_e32 v39, 0xbfb8aa3b, v39
	s_waitcnt lgkmcnt(0)
; #define LAS __attribute__((address_space(3)))
; __device__ __forceinline__ float sigmoidf_(float x) { return __builtin_amdgcn_rcpf(1.0f + __expf(-x)); }
; __device__ __forceinline__ void s5_m3(const Args& a, int l, int tile, LAS unsigned char* lds, int tid, int lane, int wave) {
;     ...
;         for (int jt = 0; jt < 8; ++jt) {
;             const int j0 = jh * 128 + jt * 16 + 4 * fq;
;             const f32x4 bg = *(const f32x4*)(a.in[16] + (size_t)l * 256 + j0);
;             const u32x2 yr = *(const LAS u32x2*)(lds + OFF_YS + (t * 264 + j0) * 2);
;             f32x4 o;
;             o.x = __uint_as_float(yr.x << 16) * sigmoidf_(acc[jt].x + bg.x); o.y = __uint_as_float(yr.x & 0xffff0000u) * sigmoidf_(acc[jt].y + bg.y);
;             o.z = __uint_as_float(yr.y << 16) * sigmoidf_(acc[jt].z + bg.z); o.w = __uint_as_float(yr.y & 0xffff0000u) * sigmoidf_(acc[jt].w + bg.w);
;             acc[jt] = o; ss += (o.x * o.x + o.y * o.y) + (o.z * o.z + o.w * o.w);
	v_lshlrev_b32_e32 v37, 16, v28
	v_mul_f32_e32 v37, v38, v37
	v_add_f32_e32 v38, v63, v199
	v_mul_f32_e32 v38, 0xbfb8aa3b, v38
	v_exp_f32_e32 v38, v38
	v_exp_f32_e32 v39, v39
	v_and_b32_e32 v28, 0xffff0000, v28
	s_waitcnt vmcnt(5)
	v_mfma_f32_16x16x32_bf16 v[0:3], v[158:161], v[58:61], v[54:57]
	v_add_f32_e32 v38, 1.0, v38
	v_rcp_f32_e32 v38, v38
	v_add_f32_e32 v39, 1.0, v39
	v_rcp_f32_e32 v39, v39
	v_mul_f32_e32 v28, v38, v28
	v_lshlrev_b32_e32 v38, 16, v29
	v_mul_f32_e32 v38, v39, v38
	v_add_f32_e32 v39, v65, v201
	v_mul_f32_e32 v39, 0xbfb8aa3b, v39
	v_exp_f32_e32 v39, v39
	v_and_b32_e32 v29, 0xffff0000, v29
	v_add_f32_e32 v39, 1.0, v39
	v_rcp_f32_e32 v39, v39
	s_waitcnt vmcnt(4)
	v_add_f32_e32 v24, v24, v202
	v_mul_f32_e32 v24, 0xbfb8aa3b, v24
	v_add_f32_e32 v25, v25, v203
	v_exp_f32_e32 v24, v24
	v_mul_f32_e32 v25, 0xbfb8aa3b, v25
	v_exp_f32_e32 v25, v25
	v_mul_f32_e32 v29, v39, v29
	v_add_f32_e32 v24, 1.0, v24
	v_rcp_f32_e32 v24, v24
	v_add_f32_e32 v25, 1.0, v25
	v_mul_f32_e32 v39, v28, v28
	v_mul_f32_e32 v40, v29, v29
	v_rcp_f32_e32 v25, v25
	v_fmac_f32_e32 v39, v37, v37
	v_fmac_f32_e32 v40, v38, v38
	v_add_f32_e32 v46, v39, v40
	v_lshlrev_b32_e32 v39, 16, v30
	v_mul_f32_e32 v39, v24, v39
	v_and_b32_e32 v24, 0xffff0000, v30
	v_mul_f32_e32 v30, v25, v24
	v_add_f32_e32 v25, v26, v204
	v_mul_f32_e32 v25, 0xbfb8aa3b, v25
	v_exp_f32_e32 v25, v25
	v_lshlrev_b32_e32 v24, 16, v31
	v_add_f32_e32 v25, 1.0, v25
	v_rcp_f32_e32 v25, v25
	s_nop 0
	v_mul_f32_e32 v40, v25, v24
	v_add_f32_e32 v25, v27, v205
	v_mul_f32_e32 v25, 0xbfb8aa3b, v25
	v_exp_f32_e32 v25, v25
	v_and_b32_e32 v24, 0xffff0000, v31
	v_add_f32_e32 v25, 1.0, v25
	v_rcp_f32_e32 v25, v25
	s_waitcnt vmcnt(3)
	v_add_f32_e32 v20, v20, v206
	v_add_f32_e32 v21, v21, v207
	v_add_f32_e32 v22, v22, v208
	v_add_f32_e32 v23, v23, v209
	v_mul_f32_e32 v31, v25, v24
	v_mul_f32_e32 v21, 0xbfb8aa3b, v21
	v_mul_f32_e32 v24, v30, v30
	v_mul_f32_e32 v25, v31, v31
	v_exp_f32_e32 v21, v21
	v_mul_f32_e32 v22, 0xbfb8aa3b, v22
	v_fmac_f32_e32 v24, v39, v39
	v_fmac_f32_e32 v25, v40, v40
	v_exp_f32_e32 v22, v22
	v_mul_f32_e32 v23, 0xbfb8aa3b, v23
	v_add_f32_e32 v24, v24, v25
	v_mul_f32_e32 v20, 0xbfb8aa3b, v20
	v_exp_f32_e32 v23, v23
	v_add_f32_e32 v46, v46, v24
	ds_read2_b64 v[24:27], v41 offset0:8 offset1:12
	v_exp_f32_e32 v20, v20
	v_add_f32_e32 v21, 1.0, v21
	v_rcp_f32_e32 v21, v21
	v_add_f32_e32 v22, 1.0, v22
	v_rcp_f32_e32 v22, v22
	v_add_f32_e32 v23, 1.0, v23
	v_add_f32_e32 v20, 1.0, v20
	v_rcp_f32_e32 v23, v23
	s_waitcnt lgkmcnt(0)
	v_lshlrev_b32_e32 v47, 16, v24
	v_rcp_f32_e32 v20, v20
	v_and_b32_e32 v24, 0xffff0000, v24
	v_mul_f32_e32 v21, v21, v24
	v_lshlrev_b32_e32 v24, 16, v25
	v_mul_f32_e32 v22, v22, v24
	v_and_b32_e32 v24, 0xffff0000, v25
	v_mul_f32_e32 v23, v23, v24
	v_mul_f32_e32 v20, v20, v47
	v_mul_f32_e32 v24, v21, v21
	v_mul_f32_e32 v25, v23, v23
	v_fmac_f32_e32 v24, v20, v20
	v_fmac_f32_e32 v25, v22, v22
	v_add_f32_e32 v24, v24, v25
	v_add_f32_e32 v46, v46, v24
	v_lshlrev_b32_e32 v24, 16, v26
	s_waitcnt vmcnt(2)
	v_add_f32_e32 v16, v16, v210
	v_mul_f32_e32 v16, 0xbfb8aa3b, v16
	v_add_f32_e32 v17, v17, v211
	v_exp_f32_e32 v16, v16
	v_mul_f32_e32 v17, 0xbfb8aa3b, v17
	v_exp_f32_e32 v17, v17
	v_add_f32_e32 v16, 1.0, v16
	v_rcp_f32_e32 v16, v16
	v_add_f32_e32 v17, 1.0, v17
	v_rcp_f32_e32 v17, v17
	v_mul_f32_e32 v24, v16, v24
	v_and_b32_e32 v16, 0xffff0000, v26
	v_mul_f32_e32 v25, v17, v16
	v_add_f32_e32 v17, v18, v212
	v_mul_f32_e32 v17, 0xbfb8aa3b, v17
	v_exp_f32_e32 v17, v17
	v_lshlrev_b32_e32 v16, 16, v27
	v_add_f32_e32 v17, 1.0, v17
	v_rcp_f32_e32 v17, v17
	s_nop 0
	v_mul_f32_e32 v26, v17, v16
	v_add_f32_e32 v17, v19, v213
	v_mul_f32_e32 v17, 0xbfb8aa3b, v17
	v_exp_f32_e32 v17, v17
	v_and_b32_e32 v16, 0xffff0000, v27
	v_add_f32_e32 v17, 1.0, v17
	v_rcp_f32_e32 v17, v17
	s_waitcnt vmcnt(1)
	v_add_f32_e32 v12, v12, v214
	v_add_f32_e32 v13, v13, v215
	v_add_f32_e32 v14, v14, v216
	v_add_f32_e32 v15, v15, v217
	v_mul_f32_e32 v27, v17, v16
	v_mul_f32_e32 v13, 0xbfb8aa3b, v13
	v_mul_f32_e32 v16, v25, v25
	v_mul_f32_e32 v17, v27, v27
	v_exp_f32_e32 v13, v13
	v_mul_f32_e32 v14, 0xbfb8aa3b, v14
	v_fmac_f32_e32 v16, v24, v24
	v_fmac_f32_e32 v17, v26, v26
	v_exp_f32_e32 v14, v14
	v_mul_f32_e32 v15, 0xbfb8aa3b, v15
	v_add_f32_e32 v16, v16, v17
	v_mul_f32_e32 v12, 0xbfb8aa3b, v12
	v_exp_f32_e32 v15, v15
	v_add_f32_e32 v46, v46, v16
	ds_read2_b64 v[16:19], v41 offset0:16 offset1:20
	v_exp_f32_e32 v12, v12
	v_add_f32_e32 v13, 1.0, v13
	v_rcp_f32_e32 v13, v13
	v_add_f32_e32 v14, 1.0, v14
	v_rcp_f32_e32 v14, v14
	v_add_f32_e32 v15, 1.0, v15
	v_add_f32_e32 v12, 1.0, v12
	v_rcp_f32_e32 v15, v15
	s_waitcnt lgkmcnt(0)
; #define LAS __attribute__((address_space(3)))
; __device__ __forceinline__ float sigmoidf_(float x) { return __builtin_amdgcn_rcpf(1.0f + __expf(-x)); }
; __device__ __forceinline__ void s5_m3(const Args& a, int l, int tile, LAS unsigned char* lds, int tid, int lane, int wave) {
;     ...
;         for (int jt = 0; jt < 8; ++jt) {
;             const int j0 = jh * 128 + jt * 16 + 4 * fq;
;             const f32x4 bg = *(const f32x4*)(a.in[16] + (size_t)l * 256 + j0);
;             const u32x2 yr = *(const LAS u32x2*)(lds + OFF_YS + (t * 264 + j0) * 2);
;             f32x4 o;
;             o.x = __uint_as_float(yr.x << 16) * sigmoidf_(acc[jt].x + bg.x); o.y = __uint_as_float(yr.x & 0xffff0000u) * sigmoidf_(acc[jt].y + bg.y);
;             o.z = __uint_as_float(yr.y << 16) * sigmoidf_(acc[jt].z + bg.z); o.w = __uint_as_float(yr.y & 0xffff0000u) * sigmoidf_(acc[jt].w + bg.w);
;             acc[jt] = o; ss += (o.x * o.x + o.y * o.y) + (o.z * o.z + o.w * o.w);
;         }
;         ss += __shfl_xor(ss, 16); ss += __shfl_xor(ss, 32);
;         LAS float* red = (LAS float*)(lds + OFF_RED2);
;         if (fq == 0) red[t * 2 + jh] = ss;
	v_lshlrev_b32_e32 v47, 16, v16
	v_rcp_f32_e32 v12, v12
	v_and_b32_e32 v16, 0xffff0000, v16
	v_mul_f32_e32 v13, v13, v16
	v_lshlrev_b32_e32 v16, 16, v17
	v_mul_f32_e32 v14, v14, v16
	v_and_b32_e32 v16, 0xffff0000, v17
	v_mul_f32_e32 v15, v15, v16
	v_mul_f32_e32 v12, v12, v47
	v_mul_f32_e32 v16, v13, v13
	v_mul_f32_e32 v17, v15, v15
	v_fmac_f32_e32 v16, v12, v12
	v_fmac_f32_e32 v17, v14, v14
	v_add_f32_e32 v16, v16, v17
	v_add_f32_e32 v46, v46, v16
	v_lshlrev_b32_e32 v16, 16, v18
	s_waitcnt vmcnt(0)
	v_add_f32_e32 v8, v8, v218
	v_mul_f32_e32 v8, 0xbfb8aa3b, v8
	v_add_f32_e32 v9, v9, v219
	v_exp_f32_e32 v8, v8
	v_mul_f32_e32 v9, 0xbfb8aa3b, v9
	v_exp_f32_e32 v9, v9
	v_add_f32_e32 v8, 1.0, v8
	v_rcp_f32_e32 v8, v8
	v_add_f32_e32 v9, 1.0, v9
	v_rcp_f32_e32 v9, v9
	v_mul_f32_e32 v16, v8, v16
	v_and_b32_e32 v8, 0xffff0000, v18
	v_mul_f32_e32 v17, v9, v8
	v_add_f32_e32 v9, v10, v220
	v_mul_f32_e32 v9, 0xbfb8aa3b, v9
	v_exp_f32_e32 v9, v9
	v_lshlrev_b32_e32 v8, 16, v19
	v_add_f32_e32 v9, 1.0, v9
	v_rcp_f32_e32 v9, v9
	s_nop 0
	v_mul_f32_e32 v18, v9, v8
	v_add_f32_e32 v9, v11, v221
	global_load_dwordx4 v[42:45], v[34:35], off offset:384
	v_mul_f32_e32 v9, 0xbfb8aa3b, v9
	v_exp_f32_e32 v9, v9
	v_and_b32_e32 v8, 0xffff0000, v19
	v_add_f32_e32 v9, 1.0, v9
	v_rcp_f32_e32 v9, v9
	s_waitcnt vmcnt(0)
	v_add_f32_e32 v4, v4, v42
	v_mul_f32_e32 v19, v9, v8
	v_mul_f32_e32 v4, 0xbfb8aa3b, v4
	v_add_f32_e32 v5, v5, v43
	v_mul_f32_e32 v8, v17, v17
	v_mul_f32_e32 v9, v19, v19
	v_exp_f32_e32 v4, v4
	v_mul_f32_e32 v5, 0xbfb8aa3b, v5
	v_fmac_f32_e32 v8, v16, v16
	v_fmac_f32_e32 v9, v18, v18
	v_exp_f32_e32 v5, v5
	v_add_f32_e32 v8, v8, v9
	v_add_f32_e32 v46, v46, v8
	ds_read2_b64 v[8:11], v41 offset0:24 offset1:28
	v_add_f32_e32 v4, 1.0, v4
	v_rcp_f32_e32 v4, v4
	v_add_f32_e32 v5, 1.0, v5
	v_rcp_f32_e32 v5, v5
	s_waitcnt lgkmcnt(0)
	v_lshlrev_b32_e32 v41, 16, v8
	v_mul_f32_e32 v41, v4, v41
	v_and_b32_e32 v4, 0xffff0000, v8
	v_mul_f32_e32 v8, v5, v4
	v_add_f32_e32 v5, v6, v44
	v_mul_f32_e32 v5, 0xbfb8aa3b, v5
	v_exp_f32_e32 v5, v5
	v_lshlrev_b32_e32 v4, 16, v9
	v_add_f32_e32 v5, 1.0, v5
	v_rcp_f32_e32 v5, v5
	s_nop 0
	v_mul_f32_e32 v42, v5, v4
	v_add_f32_e32 v5, v7, v45
	v_mul_f32_e32 v5, 0xbfb8aa3b, v5
	v_exp_f32_e32 v5, v5
	v_and_b32_e32 v4, 0xffff0000, v9
	v_add_f32_e32 v5, 1.0, v5
	v_rcp_f32_e32 v5, v5
	s_nop 0
	v_mul_f32_e32 v9, v5, v4
	v_mul_f32_e32 v4, v8, v8
	v_mul_f32_e32 v5, v9, v9
	v_fmac_f32_e32 v4, v41, v41
	v_fmac_f32_e32 v5, v42, v42
	v_add_f32_e32 v4, v4, v5
	v_add_f32_e32 v43, v46, v4
	global_load_dwordx4 v[4:7], v[34:35], off offset:448
	v_lshlrev_b32_e32 v34, 16, v10
	s_waitcnt vmcnt(0)
	v_add_f32_e32 v1, v1, v5
	v_mul_f32_e32 v1, 0xbfb8aa3b, v1
	v_add_f32_e32 v2, v2, v6
	v_exp_f32_e32 v1, v1
	v_mul_f32_e32 v2, 0xbfb8aa3b, v2
	v_add_f32_e32 v3, v3, v7
	v_add_f32_e32 v0, v0, v4
	v_exp_f32_e32 v2, v2
	v_mul_f32_e32 v3, 0xbfb8aa3b, v3
	v_mul_f32_e32 v0, 0xbfb8aa3b, v0
	v_exp_f32_e32 v3, v3
	v_exp_f32_e32 v0, v0
	v_add_f32_e32 v1, 1.0, v1
	v_rcp_f32_e32 v1, v1
	v_add_f32_e32 v2, 1.0, v2
	v_rcp_f32_e32 v2, v2
	v_add_f32_e32 v3, 1.0, v3
	v_add_f32_e32 v0, 1.0, v0
	v_rcp_f32_e32 v3, v3
	v_rcp_f32_e32 v0, v0
	v_and_b32_e32 v4, 0xffff0000, v10
	v_mul_f32_e32 v1, v1, v4
	v_lshlrev_b32_e32 v4, 16, v11
	v_mul_f32_e32 v2, v2, v4
	v_and_b32_e32 v4, 0xffff0000, v11
	v_mul_f32_e32 v3, v3, v4
	v_mul_f32_e32 v0, v0, v34
	v_mul_f32_e32 v4, v1, v1
	v_mul_f32_e32 v5, v3, v3
	v_fmac_f32_e32 v4, v0, v0
	v_fmac_f32_e32 v5, v2, v2
	v_add_f32_e32 v4, v4, v5
	v_add_f32_e32 v4, v43, v4
	ds_bpermute_b32 v5, v124, v4
	s_waitcnt lgkmcnt(0)
	v_add_f32_e32 v5, v4, v5
	ds_bpermute_b32 v6, v125, v5
	v_lshlrev_b32_e32 v4, 3, v36
	s_and_saveexec_b64 s[0:1], vcc
	s_cbranch_execz .LBB0_1443
	s_lshl_b32 s4, s4, 2
	s_add_i32 s4, s4, 0
	s_waitcnt lgkmcnt(0)
	v_add_f32_e32 v5, v5, v6
	v_add_u32_e32 v6, s4, v4
	v_add_u32_e32 v6, 0x21400, v6
	ds_write_b32 v6, v5
	s_branch .LBB0_1443

; template <class Epi, class Sched, bool ALIGN_EPI = false, bool SP2 = false>
; __device__ __forceinline__ void gemm_phase(PG8_LAS unsigned char* lds, const Gemm g, const Sched& S, const Epi& E) {
;     ...
;         const bool has_next = S.next(ui + 1, nxt);
;         const char* nA = has_next ? (const char*)g.A + (size_t)nxt.pm * tstep : cA; const char* nB = has_next ? (const char*)g.Bt + (size_t)nxt.pn * tstep : cB;
;         for (int t = 0; t < nt; t += 2) {
;             const bool last = (t == nt - 2);
;             const char* a1 = cA + (size_t)(t + 1) * kstep;
;             const char* a2 = last ? nA : cA + (size_t)(t + 2) * kstep; const char* b2 = last ? nB : cB + (size_t)(t + 2) * kstep;
;             const char* a3 = a2 + kstep; const char* b3 = b2 + kstep;
;             if (last && has_next) S.a_ready(nxt);
;             if (last) E.pre(cur, wid, lane);
;     __device__ __forceinline__ void finish(f32x4 (&acc)[2][2][4][2], const Pre&) const {
; #pragma unroll
;         for (int a = 0; a < 2; ++a)
; #pragma unroll
;             for (int b = 0; b < 2; ++b)
; #pragma unroll
;                 for (int m = 0; m < 4; ++m)
; #pragma unroll
;                     for (int n = 0; n < 2; ++n) acc[a][b][m][n] = (f32x4){0.f, 0.f, 0.f, 0.f};
;     }
.LBB0_1646:
	s_ashr_i32 s47, s46, 31
	s_lshl_b64 s[6:7], s[46:47], 19
	s_add_u32 s48, s10, s6
	s_addc_u32 s49, s11, s7
	s_and_b64 s[6:7], s[36:37], exec
	s_cselect_b32 s39, s49, s5
	s_cselect_b32 s47, s48, s4
	s_ashr_i32 s45, s44, 31
	s_lshl_b64 s[6:7], s[44:45], 19
	s_add_u32 s50, s24, s6
	s_addc_u32 s51, s25, s7
	s_and_b64 s[6:7], s[36:37], exec
	s_cselect_b32 s53, s51, s1
	s_cselect_b32 s54, s50, s0
	s_lshl_b32 s45, s55, 8
	v_add_u32_e32 v0, s45, v167
	v_ashrrev_i32_e32 v1, 31, v0
	v_lshlrev_b64 v[2:3], 6, v[0:1]
	v_or_b32_e32 v0, 16, v0
	v_ashrrev_i32_e32 v1, 31, v0
	s_add_u32 s4, s4, 0x40080
	v_lshlrev_b64 v[0:1], 6, v[0:1]
	s_addc_u32 s5, s5, 0
	v_lshl_add_u64 v[128:129], v[156:157], 0, v[0:1]
	s_add_u32 s55, s0, 0x100
	v_mov_b32_e32 v0, 0
	v_lshl_add_u64 v[130:131], v[156:157], 0, v[2:3]
	s_addc_u32 s56, s1, 0
	s_mov_b32 s57, -2
	v_mov_b32_e32 v1, 0
	v_pk_mov_b32 v[2:3], v[0:1], v[0:1]
	v_pk_mov_b32 v[4:5], v[0:1], v[0:1]
	v_pk_mov_b32 v[6:7], v[0:1], v[0:1]
	v_pk_mov_b32 v[8:9], v[0:1], v[0:1]
	v_pk_mov_b32 v[10:11], v[0:1], v[0:1]
	v_pk_mov_b32 v[12:13], v[0:1], v[0:1]
	v_pk_mov_b32 v[14:15], v[0:1], v[0:1]
	v_pk_mov_b32 v[16:17], v[0:1], v[0:1]
	v_pk_mov_b32 v[18:19], v[0:1], v[0:1]
	v_pk_mov_b32 v[20:21], v[0:1], v[0:1]
	v_pk_mov_b32 v[22:23], v[0:1], v[0:1]
	v_pk_mov_b32 v[24:25], v[0:1], v[0:1]
	v_pk_mov_b32 v[26:27], v[0:1], v[0:1]
	v_pk_mov_b32 v[28:29], v[0:1], v[0:1]
	v_pk_mov_b32 v[30:31], v[0:1], v[0:1]
	v_pk_mov_b32 v[32:33], v[0:1], v[0:1]
	v_pk_mov_b32 v[34:35], v[0:1], v[0:1]
	v_pk_mov_b32 v[36:37], v[0:1], v[0:1]
	v_pk_mov_b32 v[38:39], v[0:1], v[0:1]
	v_pk_mov_b32 v[40:41], v[0:1], v[0:1]
	v_pk_mov_b32 v[42:43], v[0:1], v[0:1]
	v_pk_mov_b32 v[44:45], v[0:1], v[0:1]
	v_pk_mov_b32 v[46:47], v[0:1], v[0:1]
	v_pk_mov_b32 v[48:49], v[0:1], v[0:1]
	v_pk_mov_b32 v[50:51], v[0:1], v[0:1]
	v_pk_mov_b32 v[52:53], v[0:1], v[0:1]
	v_pk_mov_b32 v[54:55], v[0:1], v[0:1]
	v_pk_mov_b32 v[56:57], v[0:1], v[0:1]
	v_pk_mov_b32 v[58:59], v[0:1], v[0:1]
	v_pk_mov_b32 v[60:61], v[0:1], v[0:1]
	v_pk_mov_b32 v[62:63], v[0:1], v[0:1]
	v_pk_mov_b32 v[64:65], v[0:1], v[0:1]
	v_pk_mov_b32 v[66:67], v[0:1], v[0:1]
	v_pk_mov_b32 v[68:69], v[0:1], v[0:1]
	v_pk_mov_b32 v[70:71], v[0:1], v[0:1]
	v_pk_mov_b32 v[72:73], v[0:1], v[0:1]
	v_pk_mov_b32 v[74:75], v[0:1], v[0:1]
	v_pk_mov_b32 v[76:77], v[0:1], v[0:1]
	v_pk_mov_b32 v[78:79], v[0:1], v[0:1]
	v_pk_mov_b32 v[80:81], v[0:1], v[0:1]
	v_pk_mov_b32 v[82:83], v[0:1], v[0:1]
	v_pk_mov_b32 v[84:85], v[0:1], v[0:1]
	v_pk_mov_b32 v[86:87], v[0:1], v[0:1]
	v_pk_mov_b32 v[88:89], v[0:1], v[0:1]
	v_pk_mov_b32 v[90:91], v[0:1], v[0:1]
	v_pk_mov_b32 v[92:93], v[0:1], v[0:1]
	v_pk_mov_b32 v[94:95], v[0:1], v[0:1]
	v_pk_mov_b32 v[96:97], v[0:1], v[0:1]
	v_pk_mov_b32 v[98:99], v[0:1], v[0:1]
	v_pk_mov_b32 v[100:101], v[0:1], v[0:1]
	v_pk_mov_b32 v[102:103], v[0:1], v[0:1]
	v_pk_mov_b32 v[104:105], v[0:1], v[0:1]
	v_pk_mov_b32 v[106:107], v[0:1], v[0:1]
	v_pk_mov_b32 v[108:109], v[0:1], v[0:1]
	v_pk_mov_b32 v[110:111], v[0:1], v[0:1]
	v_pk_mov_b32 v[112:113], v[0:1], v[0:1]
	v_pk_mov_b32 v[114:115], v[0:1], v[0:1]
	v_pk_mov_b32 v[116:117], v[0:1], v[0:1]
	v_pk_mov_b32 v[118:119], v[0:1], v[0:1]
	v_pk_mov_b32 v[120:121], v[0:1], v[0:1]
	v_pk_mov_b32 v[122:123], v[0:1], v[0:1]
	v_pk_mov_b32 v[124:125], v[0:1], v[0:1]
	v_pk_mov_b32 v[126:127], v[0:1], v[0:1]
	s_branch .LBB0_1648
